# hg_item(true) chunk loop: next-chunk loads no longer waited right after issue (fp16->f32 converts deferred to end of iteration, raw words parked in v240-247); loop-invariant hg_norm_g loads hoisted ou
# speedup vs baseline: 1.0126x; 1.0126x over previous
; template <bool FULL, bool STORE = true>
; __device__ __forceinline__ void hg_item(const Prm& P, LAS unsigned char* lds, int item, int wave) {
;     ...
;     HG_LOADS(0);
.LBB0_838:
	s_or_b64 exec, exec, s[18:19]
	s_ashr_i32 s84, s91, 6
	s_and_b32 s18, s2, 7
	s_ashr_i32 s85, s84, 31
	s_lshl_b32 s33, s18, 21
	s_lshl_b32 s19, s54, 1
	s_lshl_b32 s87, s18, 10
	s_lshl_b64 s[52:53], s[84:85], 13
	s_lshl_b32 s18, s26, 10
	s_and_b32 s86, s19, 0x700
	s_or_b32 s18, s52, s18
	s_add_u32 s20, s18, s55
	v_lshlrev_b32_e32 v36, 1, v32
	s_addc_u32 s21, s53, 0
	s_lshl_b32 s22, s91, 4
	s_and_b32 s74, s22, 0x380
	v_ashrrev_i32_e32 v37, 31, v36
	v_lshl_add_u64 v[76:77], v[36:37], 0, s[74:75]
	s_lshl_b64 s[20:21], s[20:21], 10
	v_lshl_add_u64 v[44:45], v[76:77], 0, s[20:21]
	v_lshlrev_b64 v[44:45], 1, v[44:45]
	v_lshl_add_u64 v[46:47], s[70:71], 0, v[44:45]
	global_load_dword v39, v[46:47], off nt
	v_lshl_add_u64 v[48:49], s[62:63], 0, v[44:45]
	global_load_dword v110, v[48:49], off nt
	v_lshl_add_u64 v[48:49], s[64:65], 0, v[44:45]
	s_mov_b64 s[20:21], 0x800
	v_ashrrev_i32_e32 v38, 3, v38
	s_mov_b32 s19, s53
	v_lshlrev_b32_e32 v43, 4, v32
	v_and_b32_e32 v94, 0x70, v43
	v_lshlrev_b32_e32 v74, 1, v94
	v_and_b32_e32 v60, 64, v108
	v_xor_b32_e32 v59, 1, v108
	v_add_u32_e32 v60, 64, v60
	v_cmp_lt_i32_e32 vcc, v59, v60
	v_lshlrev_b32_e32 v128, 4, v40
	v_readlane_b32 s46, v255, 48
	v_cndmask_b32_e32 v59, v108, v59, vcc
	v_lshlrev_b32_e32 v129, 2, v59
	v_xor_b32_e32 v59, 2, v108
	v_cmp_lt_i32_e32 vcc, v59, v60
	v_readlane_b32 s22, v255, 37
	v_readlane_b32 s24, v255, 38
	v_cndmask_b32_e32 v59, v108, v59, vcc
	v_lshlrev_b32_e32 v130, 2, v59
	v_xor_b32_e32 v59, 4, v108
	v_cmp_lt_i32_e32 vcc, v59, v60
	v_readlane_b32 s26, v255, 39
	v_readlane_b32 s28, v255, 40
	v_cndmask_b32_e32 v59, v108, v59, vcc
	v_readlane_b32 s30, v255, 41
	v_readlane_b32 s34, v255, 42
	v_readlane_b32 s36, v255, 43
	v_readlane_b32 s38, v255, 44
	v_readlane_b32 s40, v255, 45
	v_readlane_b32 s42, v255, 46
	v_readlane_b32 s44, v255, 47
	v_add_u32_e32 v96, s46, v34
	v_readlane_b32 s48, v255, 49
	v_readlane_b32 s50, v255, 50
	v_add_u32_e32 v61, s97, v34
	v_add_u32_e32 v63, s22, v34
	v_add_u32_e32 v64, s24, v34
	v_add_u32_e32 v65, s26, v34
	v_add_u32_e32 v66, s28, v34
	v_add_u32_e32 v67, s30, v34
	v_add_u32_e32 v68, s34, v34
	v_add_u32_e32 v69, s36, v34
	v_add_u32_e32 v70, s38, v34
	v_add_u32_e32 v71, s40, v34
	v_add_u32_e32 v72, s42, v34
	v_add_u32_e32 v73, s44, v34
	v_mul_lo_u32 v102, v96, s72
	v_lshlrev_b32_e32 v131, 2, v59
	v_or_b32_e32 v59, s97, v42
	v_lshlrev_b32_e32 v126, 3, v32
	v_mul_lo_u32 v58, v38, s94
	v_mul_u32_u24_e32 v41, 0x110, v33
	v_add_u32_e32 v58, 0, v58
	v_mad_u32_u24 v59, v59, s3, 0
	v_add_u32_e32 v133, v59, v128
	v_add_u32_e32 v156, v35, v41
	s_waitcnt vmcnt(1)
	v_cvt_f32_f16_e32 v78, v39
	v_cvt_f32_f16_sdwa v79, v39 dst_sel:DWORD dst_unused:UNUSED_PAD src0_sel:WORD_1
	global_load_dword v111, v[48:49], off nt
	global_load_dword v39, v[46:47], off offset:2048 nt
	v_lshl_add_u64 v[46:47], v[44:45], 0, s[20:21]
	v_lshl_add_u64 v[48:49], s[62:63], 0, v[46:47]
	v_lshl_add_u64 v[46:47], s[64:65], 0, v[46:47]
	s_mov_b64 s[20:21], 0x1000
	global_load_dword v112, v[48:49], off nt
	global_load_dword v113, v[46:47], off nt
	v_lshl_add_u64 v[46:47], v[44:45], 0, s[20:21]
	v_lshl_add_u64 v[48:49], s[70:71], 0, v[46:47]
	s_mov_b64 s[20:21], 0x1800
	s_waitcnt vmcnt(2)
	v_cvt_f32_f16_e32 v80, v39
	v_cvt_f32_f16_sdwa v81, v39 dst_sel:DWORD dst_unused:UNUSED_PAD src0_sel:WORD_1
	global_load_dword v39, v[48:49], off nt
	v_lshl_add_u64 v[48:49], s[62:63], 0, v[46:47]
	v_lshl_add_u64 v[46:47], s[64:65], 0, v[46:47]
	global_load_dword v114, v[48:49], off nt
	global_load_dword v115, v[46:47], off nt
	v_lshl_add_u64 v[46:47], v[44:45], 0, s[20:21]
	v_lshl_add_u64 v[48:49], s[70:71], 0, v[46:47]
	s_mov_b64 s[20:21], 0x2000
	s_waitcnt vmcnt(2)
	v_cvt_f32_f16_e32 v82, v39
	v_cvt_f32_f16_sdwa v83, v39 dst_sel:DWORD dst_unused:UNUSED_PAD src0_sel:WORD_1
	global_load_dword v39, v[48:49], off nt
	v_lshl_add_u64 v[48:49], s[62:63], 0, v[46:47]
	v_lshl_add_u64 v[46:47], s[64:65], 0, v[46:47]
	global_load_dword v116, v[48:49], off nt
	global_load_dword v117, v[46:47], off nt
	v_lshl_add_u64 v[46:47], v[44:45], 0, s[20:21]
	v_lshl_add_u64 v[48:49], s[70:71], 0, v[46:47]
	s_mov_b64 s[20:21], 0x2800
	s_waitcnt vmcnt(2)
	v_cvt_f32_f16_e32 v84, v39
	v_cvt_f32_f16_sdwa v85, v39 dst_sel:DWORD dst_unused:UNUSED_PAD src0_sel:WORD_1
	global_load_dword v39, v[48:49], off nt
	v_lshl_add_u64 v[48:49], s[62:63], 0, v[46:47]
	v_lshl_add_u64 v[46:47], s[64:65], 0, v[46:47]
	global_load_dword v118, v[48:49], off nt
	global_load_dword v119, v[46:47], off nt
	v_lshl_add_u64 v[46:47], v[44:45], 0, s[20:21]
	v_lshl_add_u64 v[48:49], s[70:71], 0, v[46:47]
	s_mov_b64 s[20:21], 0x3000
	s_waitcnt vmcnt(2)
	v_cvt_f32_f16_e32 v86, v39
	v_cvt_f32_f16_sdwa v87, v39 dst_sel:DWORD dst_unused:UNUSED_PAD src0_sel:WORD_1
	global_load_dword v39, v[48:49], off nt
	v_lshl_add_u64 v[48:49], s[62:63], 0, v[46:47]
	v_lshl_add_u64 v[46:47], s[64:65], 0, v[46:47]
	global_load_dword v120, v[48:49], off nt
	global_load_dword v121, v[46:47], off nt
	v_lshl_add_u64 v[46:47], v[44:45], 0, s[20:21]
	v_lshl_add_u64 v[48:49], s[70:71], 0, v[46:47]
	s_mov_b64 s[20:21], 0x3800
	v_lshl_add_u64 v[44:45], v[44:45], 0, s[20:21]
	v_readlane_b32 s20, v255, 36
	s_waitcnt vmcnt(2)
	v_cvt_f32_f16_e32 v88, v39
	v_cvt_f32_f16_sdwa v89, v39 dst_sel:DWORD dst_unused:UNUSED_PAD src0_sel:WORD_1
	global_load_dword v39, v[48:49], off nt
	v_lshl_add_u64 v[48:49], s[62:63], 0, v[46:47]
	v_lshl_add_u64 v[46:47], s[64:65], 0, v[46:47]
	global_load_dword v122, v[48:49], off nt
	global_load_dword v123, v[46:47], off nt
	v_lshl_add_u64 v[46:47], s[70:71], 0, v[44:45]
	v_add_u32_e32 v62, s20, v34
	s_waitcnt vmcnt(2)
; template <bool FULL, bool STORE = true>
; __device__ __forceinline__ void hg_item(const Prm& P, LAS unsigned char* lds, int item, int wave) {
;     ...
;                 const size_t oo = (row0 + t) * 1024 + h * 128 + vs; const float* gn = P.in[I_HGNG] + h * 128 + vs;
;                 float g0[8], g1[8]; unpack8(gcur0, g0); unpack8(gcur1, g1);
;                 float w0[8], w1[8];
; #pragma unroll
;                 for (int j = 0; j < 8; ++j) { w0[j] = o[j] * r * gn[j] * g0[j]; w1[j] = o[8 + j] * r * gn[8 + j] * g1[j]; }
	v_cvt_f32_f16_e32 v90, v39
	v_cvt_f32_f16_sdwa v91, v39 dst_sel:DWORD dst_unused:UNUSED_PAD src0_sel:WORD_1
	global_load_dword v39, v[46:47], off nt
	v_lshl_add_u64 v[46:47], s[62:63], 0, v[44:45]
	v_lshl_add_u64 v[44:45], s[64:65], 0, v[44:45]
	global_load_dword v124, v[46:47], off nt
	global_load_dword v125, v[44:45], off nt
	v_lshlrev_b32_e32 v47, 2, v32
	s_waitcnt vmcnt(2)
	v_cvt_f32_f16_e32 v92, v39
	v_cvt_f32_f16_sdwa v93, v39 dst_sel:DWORD dst_unused:UNUSED_PAD src0_sel:WORD_1
	v_ashrrev_i32_e32 v39, 31, v38
	v_lshl_add_u64 v[44:45], s[18:19], 0, v[38:39]
	v_lshlrev_b64 v[44:45], 11, v[44:45]
	v_lshl_add_u64 v[44:45], s[66:67], 0, v[44:45]
	s_lshl_b32 s18, s74, 1
	s_mov_b32 s19, s75
	v_lshl_add_u64 v[44:45], v[44:45], 0, s[18:19]
	v_lshl_add_u64 v[44:45], v[44:45], 0, v[74:75]
	global_load_dwordx4 v[48:51], v[44:45], off offset:16 nt
	global_load_dwordx4 v[52:55], v[44:45], off nt
	s_movk_i32 s18, 0x120
	v_mul_lo_u32 v127, v32, s18
	v_readlane_b32 s18, v255, 32
	s_add_i32 s19, 0, 0x15c00
	s_lshl_b32 s74, s74, 2
	v_or_b32_e32 v45, s18, v42
	s_add_i32 s18, 0, 0x11400
	v_mov_b32_e32 v40, s18
	v_add_u32_e32 v57, s18, v128
	v_readlane_b32 s18, v255, 34
	v_mov_b32_e32 v46, s19
	v_add_u32_e32 v74, s59, v34
	v_readlane_b32 s19, v255, 33
	v_or_b32_e32 v95, s18, v42
	s_add_u32 vcc_lo, s82, s74
	v_mad_u32_u24 v40, v45, s72, v40
	v_mad_u32_u24 v45, v45, s3, v46
	v_lshl_add_u32 v46, v42, 2, s19
	v_readlane_b32 s19, v255, 29
	v_cmp_gt_i32_e64 s[46:47], v95, v96
	v_add_u32_e32 v96, s48, v34
	v_add_u32_e32 v34, s50, v34
	v_mul_lo_u32 v104, v74, s94
	v_lshlrev_b32_e32 v74, 2, v94
	s_addc_u32 vcc_hi, s83, 0
	v_or_b32_e32 v44, s59, v42
	v_or_b32_e32 v56, s19, v42
	v_mad_u32_u24 v60, v95, s3, 0
	v_lshl_add_u32 v42, v95, 1, s73
	v_cmp_gt_i32_e64 s[18:19], v95, v61
	v_cmp_gt_i32_e64 s[20:21], v95, v62
	v_cmp_gt_i32_e64 s[22:23], v95, v63
	v_cmp_gt_i32_e64 s[24:25], v95, v64
	v_cmp_gt_i32_e64 s[26:27], v95, v65
	v_cmp_gt_i32_e64 s[28:29], v95, v66
	v_cmp_gt_i32_e64 s[30:31], v95, v67
	v_cmp_gt_i32_e64 s[34:35], v95, v68
	v_cmp_gt_i32_e64 s[36:37], v95, v69
	v_cmp_gt_i32_e64 s[38:39], v95, v70
	v_cmp_gt_i32_e64 s[40:41], v95, v71
	v_cmp_gt_i32_e64 s[42:43], v95, v72
	v_cmp_gt_i32_e64 s[44:45], v95, v73
	v_cmp_gt_i32_e64 s[48:49], v95, v96
	v_cmp_gt_i32_e64 s[50:51], v95, v34
	v_lshl_add_u64 v[94:95], vcc, 0, v[74:75]
	s_lshl_b64 vcc, s[84:85], 24
	s_or_b32 vcc_lo, vcc_lo, s33
	v_readlane_b32 s33, v255, 55
	s_add_u32 s33, s33, s52
	s_addc_u32 s53, s90, s53
	v_lshlrev_b64 v[38:39], 11, v[38:39]
	v_and_b32_e32 v32, 7, v32
	s_add_u32 s52, s33, s87
	v_lshl_add_u64 v[38:39], vcc, 0, v[38:39]
	v_lshlrev_b32_e32 v32, 5, v32
	s_addc_u32 s53, s53, 0
	s_or_b32 s33, vcc_lo, s86
	v_mul_lo_u32 v43, v44, s72
	v_mul_lo_u32 v44, v44, s3
	v_mul_lo_u32 v56, v56, s72
	v_mul_lo_u32 v105, v34, s72
	v_mul_u32_u24_e32 v34, 0x90, v33
	v_or3_b32 v38, v38, s86, v32
	v_mov_b32_e32 v32, s33
	v_mov_b32_e32 v33, vcc_hi
	v_add_u32_e32 v43, s73, v43
	v_add_u32_e32 v44, 0, v44
	v_add_u32_e32 v56, 0, v56
	v_mul_lo_u32 v61, v61, s72
	v_mul_lo_u32 v62, v62, s72
	v_mul_lo_u32 v63, v63, s72
	v_mul_lo_u32 v64, v64, s72
	v_mul_lo_u32 v65, v65, s72
	v_mul_lo_u32 v66, v66, s72
	v_mul_lo_u32 v67, v67, s72
	v_mul_lo_u32 v68, v68, s72
	v_mul_lo_u32 v69, v69, s72
	v_mul_lo_u32 v70, v70, s72
	v_mul_lo_u32 v71, v71, s72
	v_mul_lo_u32 v72, v72, s72
	v_mul_lo_u32 v73, v73, s72
	v_mul_lo_u32 v103, v96, s72
	v_lshl_add_u64 v[32:33], v[36:37], 1, v[32:33]
	v_readlane_b32 s33, v255, 51
	v_lshl_add_u64 v[96:97], s[92:93], 0, v[38:39]
	s_lshl_b64 s[84:85], s[52:53], 10
	v_lshl_add_u64 v[98:99], s[78:79], 0, v[32:33]
	v_lshl_add_u64 v[100:101], s[80:81], 0, v[32:33]
	s_mov_b64 s[86:87], 0
	v_add_u32_e32 v132, s33, v47
	v_add_u32_e32 v134, v60, v128
	v_add_u32_e32 v135, v42, v61
	v_add_u32_e32 v136, v42, v62
	v_add_u32_e32 v137, v42, v63
	v_add_u32_e32 v138, v42, v64
	v_add_u32_e32 v139, v42, v65
	v_add_u32_e32 v140, v42, v66
	v_add_u32_e32 v141, v42, v67
	v_add_u32_e32 v142, v42, v68
	v_add_u32_e32 v143, v42, v69
	v_add_u32_e32 v144, v42, v70
	v_add_u32_e32 v145, v42, v71
	v_add_u32_e32 v146, v42, v72
	v_add_u32_e32 v147, v42, v73
	v_add_u32_e32 v148, v42, v102
	v_add_u32_e32 v149, v42, v103
	v_add_u32_e32 v150, v42, v105
	v_add_u32_e32 v151, v44, v128
	v_add_u32_e32 v152, v45, v128
	v_add_u32_e32 v153, v46, v104
	v_add_u32_e32 v154, v56, v128
	v_add_u32_e32 v155, v57, v34
	v_add_u32_e32 v157, v58, v74
	v_add_u32_e32 v158, v43, v128
	v_add_u32_e32 v159, v40, v128
	global_load_dwordx4 v[224:227], v[94:95], off offset:48
	global_load_dwordx4 v[228:231], v[94:95], off offset:32
	global_load_dwordx4 v[232:235], v[94:95], off offset:16
	global_load_dwordx4 v[236:239], v[94:95], off
	s_branch .LBB0_840
; #define LAS __attribute__((address_space(3)))
; template <bool FULL, bool STORE = true>
; __device__ __forceinline__ void hg_item(const Prm& P, LAS unsigned char* lds, int item, int wave) {
;     ...
;                 for (int ks = 0; ks < 8; ++ks) { const bf16x8 a = *(const LAS bf16x8*)(lds + HL_QD + (tb * 32 + l31) * 272 + ks * 32 + lh * 16), bb = *(const LAS bf16x8*)(lds + HL_ST + (vb * 32 + l31) * 272 + ks * 32 + lh * 16);
;                     o = __builtin_amdgcn_mfma_f32_32x32x16_bf16(a, bb, o, 0, 0, 0); }
; #pragma unroll
;                 for (int r = 0; r < 16; ++r) { const int t = tb * 32 + (r & 3) + 8 * (r >> 2) + 4 * lh; *(LAS float*)(lds + HL_OS + t * 528 + (vb * 32 + l31) * 4) = o[r]; }
;             }
;         }
; #pragma unroll
;         for (int g4 = 0; g4 < 4; ++g4) { const f32x4 d = *(const LAS f32x4*)(lds + HL_DC + (kb * 32 + 8 * g4 + 4 * lh) * 4);
; #pragma unroll
;             for (int i = 0; i < 2; ++i)
; #pragma unroll
;                 for (int j = 0; j < 4; ++j) S[i][4 * g4 + j] *= d[j]; }
; #pragma unroll
;         for (int ks = 0; ks < 4; ++ks) { const bf16x8 a = *(const LAS bf16x8*)(lds + HL_KDT + (kb * 32 + l31) * 144 + ks * 32 + lh * 16);
; #pragma unroll
;             for (int i = 0; i < 2; ++i) { const bf16x8 bb = *(const LAS bf16x8*)(lds + HL_IVT + ((vb0 + i) * 32 + l31) * 144 + ks * 32 + lh * 16); S[i] = __builtin_amdgcn_mfma_f32_32x32x16_bf16(a, bb, S[i], 0, 0, 0); } }
.LBB0_839:
	ds_read_b128 v[64:67], v151 offset:34816
	ds_read_b128 v[68:71], v151 offset:34848
	ds_read_b128 v[104:107], v152
	ds_read_b128 v[160:163], v152 offset:32
	s_mov_b32 s33, 0x800000
	s_add_u32 s86, s86, 0x20000
	s_addc_u32 s87, s87, 0
	s_waitcnt lgkmcnt(1)
	v_mfma_f32_32x32x16_bf16 v[32:47], v[64:67], v[104:107], v[32:47]
	v_lshlrev_b32_e32 v104, 16, v52
	v_and_b32_e32 v105, 0xffff0000, v52
	v_lshlrev_b32_e32 v52, 16, v53
	v_and_b32_e32 v53, 0xffff0000, v53
	s_add_u32 s84, s84, 0x10000
	s_addc_u32 s85, s85, 0
	s_cmp_lg_u32 s86, 0x200000
	s_waitcnt lgkmcnt(0)
	v_mfma_f32_32x32x16_bf16 v[32:47], v[68:71], v[160:163], v[32:47]
	ds_read_b128 v[64:67], v151 offset:34880
	ds_read_b128 v[68:71], v152 offset:64
	s_waitcnt lgkmcnt(0)
	v_mfma_f32_32x32x16_bf16 v[32:47], v[64:67], v[68:71], v[32:47]
	ds_read_b128 v[64:67], v151 offset:34912
	ds_read_b128 v[68:71], v152 offset:96
	s_waitcnt lgkmcnt(0)
	v_mfma_f32_32x32x16_bf16 v[32:47], v[64:67], v[68:71], v[32:47]
	ds_read_b128 v[64:67], v151 offset:34944
	ds_read_b128 v[68:71], v152 offset:128
	s_waitcnt lgkmcnt(0)
	v_mfma_f32_32x32x16_bf16 v[32:47], v[64:67], v[68:71], v[32:47]
	ds_read_b128 v[64:67], v151 offset:34976
	ds_read_b128 v[68:71], v152 offset:160
	s_waitcnt lgkmcnt(0)
	v_mfma_f32_32x32x16_bf16 v[32:47], v[64:67], v[68:71], v[32:47]
	ds_read_b128 v[64:67], v151 offset:35008
	ds_read_b128 v[68:71], v152 offset:192
	s_waitcnt lgkmcnt(0)
	v_mfma_f32_32x32x16_bf16 v[32:47], v[64:67], v[68:71], v[32:47]
	ds_read_b128 v[64:67], v151 offset:35040
	ds_read_b128 v[68:71], v152 offset:224
	s_waitcnt lgkmcnt(0)
	v_mfma_f32_32x32x16_bf16 v[32:47], v[64:67], v[68:71], v[32:47]
	s_nop 11
	ds_write2_b32 v153, v32, v33 offset1:132
	v_add_u32_e32 v32, 0x400, v153
	ds_write2_b32 v32, v34, v35 offset0:8 offset1:140
	v_add_u32_e32 v32, 0x1000, v153
	ds_write2_b32 v32, v36, v37 offset0:32 offset1:164
	v_add_u32_e32 v32, 0x1400, v153
	ds_write2_b32 v32, v38, v39 offset0:40 offset1:172
	v_add_u32_e32 v32, 0x2000, v153
	ds_write2_b32 v32, v40, v41 offset0:64 offset1:196
	v_add_u32_e32 v32, 0x2400, v153
	ds_write2_b32 v32, v42, v43 offset0:72 offset1:204
	v_add_u32_e32 v32, 0x3000, v153
	ds_write2_b32 v32, v44, v45 offset0:96 offset1:228
	v_add_u32_e32 v32, 0x3400, v153
	ds_write2_b32 v32, v46, v47 offset0:104 offset1:236
	v_add_u32_e32 v40, s96, v128
	ds_read_b128 v[32:35], v40
	ds_read_b128 v[36:39], v40 offset:32
	s_waitcnt lgkmcnt(1)
	v_pk_mul_f32 v[0:1], v[0:1], v[32:33]
	v_pk_mul_f32 v[2:3], v[2:3], v[34:35]
	v_pk_mul_f32 v[16:17], v[16:17], v[32:33]
	v_pk_mul_f32 v[18:19], v[18:19], v[34:35]
	ds_read_b128 v[32:35], v40 offset:64
	s_waitcnt lgkmcnt(1)
	v_pk_mul_f32 v[4:5], v[4:5], v[36:37]
	v_pk_mul_f32 v[6:7], v[6:7], v[38:39]
	v_pk_mul_f32 v[20:21], v[20:21], v[36:37]
	v_pk_mul_f32 v[22:23], v[22:23], v[38:39]
	s_waitcnt lgkmcnt(0)
	v_pk_mul_f32 v[8:9], v[8:9], v[32:33]
	v_pk_mul_f32 v[10:11], v[10:11], v[34:35]
	v_pk_mul_f32 v[24:25], v[24:25], v[32:33]
	v_pk_mul_f32 v[26:27], v[26:27], v[34:35]
	ds_read_b128 v[32:35], v40 offset:96
	s_waitcnt lgkmcnt(0)
	v_pk_mul_f32 v[12:13], v[12:13], v[32:33]
	v_pk_mul_f32 v[14:15], v[14:15], v[34:35]
	v_pk_mul_f32 v[28:29], v[28:29], v[32:33]
	v_pk_mul_f32 v[30:31], v[30:31], v[34:35]
	ds_read_b128 v[32:35], v154 offset:52224
	ds_read_b128 v[36:39], v154 offset:52256
	ds_read_b128 v[40:43], v155
	ds_read_b128 v[44:47], v155 offset:32
	s_waitcnt lgkmcnt(1)
	v_mfma_f32_32x32x16_bf16 v[0:15], v[32:35], v[40:43], v[0:15]
	ds_read_b128 v[40:43], v155 offset:4608
	s_waitcnt lgkmcnt(0)
	v_mfma_f32_32x32x16_bf16 v[16:31], v[32:35], v[40:43], v[16:31]
	ds_read_b128 v[32:35], v155 offset:4640
	v_mfma_f32_32x32x16_bf16 v[0:15], v[36:39], v[44:47], v[0:15]
	s_waitcnt lgkmcnt(0)
	v_mfma_f32_32x32x16_bf16 v[16:31], v[36:39], v[32:35], v[16:31]
	ds_read_b128 v[32:35], v154 offset:52288
	ds_read_b128 v[36:39], v155 offset:64
	s_waitcnt lgkmcnt(0)
	v_mfma_f32_32x32x16_bf16 v[0:15], v[32:35], v[36:39], v[0:15]
	ds_read_b128 v[36:39], v155 offset:4672
	s_waitcnt lgkmcnt(0)
	v_mfma_f32_32x32x16_bf16 v[16:31], v[32:35], v[36:39], v[16:31]
	ds_read_b128 v[32:35], v154 offset:52320
	ds_read_b128 v[36:39], v155 offset:96
	s_waitcnt lgkmcnt(0)
	v_mfma_f32_32x32x16_bf16 v[0:15], v[32:35], v[36:39], v[0:15]
	ds_read_b128 v[36:39], v155 offset:4704
	s_waitcnt lgkmcnt(0)
	s_barrier
; #define LAS __attribute__((address_space(3)))
; __device__ __forceinline__ unsigned pk2(float lo, float hi) { typedef float f2v __attribute__((ext_vector_type(2))); typedef __bf16 b2v __attribute__((ext_vector_type(2))); const f2v v = {lo, hi}; const b2v b = __builtin_convertvector(v, b2v); return __builtin_bit_cast(unsigned, b); }
; __device__ __forceinline__ u32x4 pack8(const float (&f)[8]) { u32x4 w; w.x = pk2(f[0], f[1]); w.y = pk2(f[2], f[3]); w.z = pk2(f[4], f[5]); w.w = pk2(f[6], f[7]); return w; }
; template <bool FULL, bool STORE = true>
; __device__ __forceinline__ void hg_item(const Prm& P, LAS unsigned char* lds, int item, int wave) {
;     ...
;         if (FULL) {
;             __syncthreads();
; #pragma unroll
;             for (int i = 0; i < 2; ++i)
; #pragma unroll
;                 for (int g4 = 0; g4 < 4; ++g4) { u32x2 w; w.x = pk2(S[i][4 * g4], S[i][4 * g4 + 1]); w.y = pk2(S[i][4 * g4 + 2], S[i][4 * g4 + 3]);
;                     *(LAS u32x2*)(lds + HL_ST + ((vb0 + i) * 32 + l31) * 272 + (kb * 32 + 8 * g4 + 4 * lh) * 2) = w; }
;             { const int t = tid >> 3, vs = (tid & 7) * 16; float o[16]; float ss = 0.f;
; #pragma unroll
;                 for (int q4 = 0; q4 < 4; ++q4) { const f32x4 x4 = *(const LAS f32x4*)(lds + HL_OS + t * 528 + (vs + 4 * q4) * 4);
; #pragma unroll
;                     for (int j = 0; j < 4; ++j) { o[4 * q4 + j] = x4[j]; ss += x4[j] * x4[j]; } }
;                 ss += __shfl_xor(ss, 1); ss += __shfl_xor(ss, 2); ss += __shfl_xor(ss, 4);
;                 const float r = rsqrtf(ss * (1.0f / 128.0f) + EPS);
;                 const size_t oo = (row0 + t) * 1024 + h * 128 + vs; const float* gn = P.in[I_HGNG] + h * 128 + vs;
;                 float g0[8], g1[8]; unpack8(gcur0, g0); unpack8(gcur1, g1);
;                 float w0[8], w1[8];
; #pragma unroll
;                 for (int j = 0; j < 8; ++j) { w0[j] = o[j] * r * gn[j] * g0[j]; w1[j] = o[8 + j] * r * gn[8 + j] * g1[j]; }
;                 if (STORE) { *(u32x4*)(AHG + oo) = pack8(w0); *(u32x4*)(AHG + oo + 8) = pack8(w1); }
	v_mfma_f32_32x32x16_bf16 v[16:31], v[32:35], v[36:39], v[16:31]
	s_nop 7
	v_cvt_pk_bf16_f32 v32, v0, v1
	v_cvt_pk_bf16_f32 v33, v2, v3
	v_cvt_pk_bf16_f32 v34, v4, v5
	v_cvt_pk_bf16_f32 v35, v6, v7
	ds_write2_b64 v156, v[32:33], v[34:35] offset1:2
	v_cvt_pk_bf16_f32 v32, v8, v9
	v_cvt_pk_bf16_f32 v33, v10, v11
	v_cvt_pk_bf16_f32 v34, v12, v13
	v_cvt_pk_bf16_f32 v35, v14, v15
	ds_write2_b64 v156, v[32:33], v[34:35] offset0:4 offset1:6
	v_cvt_pk_bf16_f32 v32, v16, v17
	v_cvt_pk_bf16_f32 v33, v18, v19
	v_cvt_pk_bf16_f32 v34, v20, v21
	v_cvt_pk_bf16_f32 v35, v22, v23
	v_add_u32_e32 v36, 0x2000, v156
	ds_write2_b64 v36, v[32:33], v[34:35] offset0:64 offset1:66
	v_cvt_pk_bf16_f32 v32, v24, v25
	v_cvt_pk_bf16_f32 v33, v26, v27
	v_cvt_pk_bf16_f32 v34, v28, v29
	v_cvt_pk_bf16_f32 v35, v30, v31
	ds_write2_b64 v36, v[32:33], v[34:35] offset0:68 offset1:70
	ds_read_b128 v[66:69], v157
	ds_read_b128 v[36:39], v157 offset:16
	ds_read_b128 v[44:47], v157 offset:32
	ds_read_b128 v[32:35], v157 offset:48
	s_waitcnt lgkmcnt(3)
	v_mul_f32_e32 v64, v67, v67
	v_fmac_f32_e32 v64, v66, v66
	v_fmac_f32_e32 v64, v68, v68
	v_fmac_f32_e32 v64, v69, v69
	s_waitcnt lgkmcnt(2)
	v_fmac_f32_e32 v64, v36, v36
	v_fmac_f32_e32 v64, v37, v37
	v_fmac_f32_e32 v64, v38, v38
	v_fmac_f32_e32 v64, v39, v39
	s_waitcnt lgkmcnt(1)
	v_pk_mul_f32 v[42:43], v[44:45], v[44:45]
	v_pk_mul_f32 v[40:41], v[46:47], v[46:47]
	v_add_f32_e32 v42, v42, v64
	v_add_f32_e32 v42, v43, v42
	v_add_f32_e32 v40, v40, v42
	v_add_f32_e32 v64, v41, v40
	s_waitcnt lgkmcnt(0)
	v_pk_mul_f32 v[42:43], v[32:33], v[32:33]
	v_pk_mul_f32 v[40:41], v[34:35], v[34:35]
	v_add_f32_e32 v42, v42, v64
	v_add_f32_e32 v42, v43, v42
	v_add_f32_e32 v40, v40, v42
	v_add_f32_e32 v40, v41, v40
	ds_bpermute_b32 v41, v129, v40
	s_waitcnt lgkmcnt(0)
	v_add_f32_e32 v40, v40, v41
	ds_bpermute_b32 v41, v130, v40
	s_waitcnt lgkmcnt(0)
	v_add_f32_e32 v40, v40, v41
	ds_bpermute_b32 v41, v131, v40
	s_waitcnt lgkmcnt(0)
	v_add_f32_e32 v40, v40, v41
	v_fmamk_f32 v40, v40, 0x3c000000, v109
	v_cmp_gt_f32_e32 vcc, s33, v40
	v_mul_f32_e32 v41, 0x4b800000, v40
	s_mov_b32 s33, 0x7400000
	v_cndmask_b32_e32 v40, v40, v41, vcc
	v_rsq_f32_e32 v40, v40
	s_nop 0
	v_mul_f32_e32 v41, 0x45800000, v40
	v_cndmask_b32_e32 v74, v40, v41, vcc
	v_pk_mul_f32 v[106:107], v[66:67], v[74:75] op_sel_hi:[1,0]
	v_pk_mul_f32 v[46:47], v[46:47], v[74:75] op_sel_hi:[1,0]
	v_pk_mul_f32 v[36:37], v[36:37], v[74:75] op_sel_hi:[1,0]
	v_pk_mul_f32 v[32:33], v[32:33], v[74:75] op_sel_hi:[1,0]
	v_pk_mul_f32 v[44:45], v[44:45], v[74:75] op_sel_hi:[1,0]
	v_pk_mul_f32 v[38:39], v[38:39], v[74:75] op_sel_hi:[1,0]
	v_pk_mul_f32 v[34:35], v[34:35], v[74:75] op_sel_hi:[1,0]
	s_waitcnt vmcnt(0)
	v_pk_mul_f32 v[32:33], v[224:225], v[32:33]
	v_pk_mul_f32 v[46:47], v[230:231], v[46:47]
	v_pk_mul_f32 v[36:37], v[232:233], v[36:37]
	v_pk_mul_f32 v[106:107], v[236:237], v[106:107]
	v_pk_mul_f32 v[44:45], v[228:229], v[44:45]
	v_pk_mul_f32 v[104:105], v[106:107], v[104:105]
	v_lshlrev_b32_e32 v106, 16, v48
	v_and_b32_e32 v107, 0xffff0000, v48
	v_lshlrev_b32_e32 v48, 16, v49
	v_and_b32_e32 v49, 0xffff0000, v49
	v_pk_mul_f32 v[46:47], v[46:47], v[48:49]
	v_lshlrev_b32_e32 v48, 16, v54
	v_and_b32_e32 v49, 0xffff0000, v54
	v_pk_mul_f32 v[36:37], v[36:37], v[48:49]
	v_lshlrev_b32_e32 v48, 16, v50
	v_and_b32_e32 v49, 0xffff0000, v50
	v_pk_mul_f32 v[64:65], v[68:69], v[74:75] op_sel_hi:[1,0]
	v_pk_mul_f32 v[40:41], v[32:33], v[48:49]
	v_lshlrev_b32_e32 v32, 16, v55
	v_and_b32_e32 v33, 0xffff0000, v55
	v_pk_mul_f32 v[38:39], v[234:235], v[38:39]
	v_pk_mul_f32 v[64:65], v[238:239], v[64:65]
	v_pk_mul_f32 v[38:39], v[38:39], v[32:33]
	v_lshlrev_b32_e32 v32, 16, v51
	v_and_b32_e32 v33, 0xffff0000, v51
	v_pk_mul_f32 v[34:35], v[226:227], v[34:35]
	v_pk_mul_f32 v[52:53], v[64:65], v[52:53]
	v_pk_mul_f32 v[42:43], v[34:35], v[32:33]
	v_cvt_pk_bf16_f32 v34, v36, v37
	v_add_co_u32_e32 v36, vcc, s33, v102
	v_pk_mul_f32 v[44:45], v[44:45], v[106:107]
	v_cvt_pk_bf16_f32 v32, v104, v105
	v_cvt_pk_bf16_f32 v33, v52, v53
	v_cvt_pk_bf16_f32 v35, v38, v39
	v_addc_co_u32_e32 v37, vcc, 0, v103, vcc
	v_mov_b64_e32 v[52:53], v[56:57]
	v_mov_b64_e32 v[48:49], v[60:61]
	global_store_dwordx4 v[36:37], v[32:35], off
	v_mov_b64_e32 v[54:55], v[58:59]
	v_mov_b64_e32 v[50:51], v[62:63]
	v_cvt_pk_bf16_f32 v32, v44, v45
	v_cvt_pk_bf16_f32 v33, v46, v47
	v_cvt_pk_bf16_f32 v34, v40, v41
	v_cvt_pk_bf16_f32 v35, v42, v43
	global_store_dwordx4 v[36:37], v[32:35], off offset:16
	v_cvt_f32_f16_e32 v78, v240
	v_cvt_f32_f16_sdwa v79, v240 dst_sel:DWORD dst_unused:UNUSED_PAD src0_sel:WORD_1
	v_cvt_f32_f16_e32 v80, v241
	v_cvt_f32_f16_sdwa v81, v241 dst_sel:DWORD dst_unused:UNUSED_PAD src0_sel:WORD_1
	v_cvt_f32_f16_e32 v82, v242
	v_cvt_f32_f16_sdwa v83, v242 dst_sel:DWORD dst_unused:UNUSED_PAD src0_sel:WORD_1
	v_cvt_f32_f16_e32 v84, v243
	v_cvt_f32_f16_sdwa v85, v243 dst_sel:DWORD dst_unused:UNUSED_PAD src0_sel:WORD_1
	v_cvt_f32_f16_e32 v86, v244
	v_cvt_f32_f16_sdwa v87, v244 dst_sel:DWORD dst_unused:UNUSED_PAD src0_sel:WORD_1
	v_cvt_f32_f16_e32 v88, v245
	v_cvt_f32_f16_sdwa v89, v245 dst_sel:DWORD dst_unused:UNUSED_PAD src0_sel:WORD_1
	v_cvt_f32_f16_e32 v90, v246
	v_cvt_f32_f16_sdwa v91, v246 dst_sel:DWORD dst_unused:UNUSED_PAD src0_sel:WORD_1
	v_cvt_f32_f16_e32 v92, v247
	v_cvt_f32_f16_sdwa v93, v247 dst_sel:DWORD dst_unused:UNUSED_PAD src0_sel:WORD_1
	s_cbranch_scc0 .LBB0_821

; template <bool FULL, bool STORE = true>
; __device__ __forceinline__ void hg_item(const Prm& P, LAS unsigned char* lds, int item, int wave) {
;     ...
;         const u32x4 gcur0 = ghw0, gcur1 = ghw1;
;         if (ch + 1 < 16) HG_LOADS(ch + 1);
.LBB0_842:
	s_waitcnt vmcnt(1)
	v_mov_b64_e32 v[62:63], v[50:51]
	s_waitcnt vmcnt(0)
	v_mov_b64_e32 v[58:59], v[54:55]
	s_cmp_eq_u32 s86, 0x1e0000
	v_lshl_add_u64 v[102:103], v[96:97], 0, s[86:87]
	v_mov_b64_e32 v[60:61], v[48:49]
	v_mov_b64_e32 v[56:57], v[52:53]
	s_cbranch_scc1 .LBB0_844
	v_lshl_add_u64 v[32:33], v[98:99], 0, s[86:87]
	global_load_dword v240, v[32:33], off nt
	v_lshl_add_u64 v[32:33], v[100:101], 0, s[86:87]
	v_add_co_u32_e32 v34, vcc, 0xf420000, v32
	s_or_b32 s52, s84, 0x400
	s_nop 0
	v_addc_co_u32_e32 v35, vcc, 0, v33, vcc
	v_add_co_u32_e32 v32, vcc, 0x7420000, v32
	s_mov_b32 s53, s85
	s_nop 0
	v_addc_co_u32_e32 v33, vcc, 0, v33, vcc
	global_load_dword v110, v[34:35], off nt
	global_load_dword v111, v[32:33], off nt
	v_lshl_add_u64 v[32:33], s[52:53], 0, v[76:77]
	v_lshlrev_b64 v[32:33], 1, v[32:33]
	v_lshl_add_u64 v[34:35], s[70:71], 0, v[32:33]
	global_load_dword v241, v[34:35], off nt
	v_lshl_add_u64 v[34:35], s[62:63], 0, v[32:33]
	v_lshl_add_u64 v[32:33], s[64:65], 0, v[32:33]
	s_or_b32 s52, s84, 0x800
	global_load_dword v112, v[34:35], off nt
	global_load_dword v113, v[32:33], off nt
	v_lshl_add_u64 v[32:33], s[52:53], 0, v[76:77]
	v_lshlrev_b64 v[32:33], 1, v[32:33]
	v_lshl_add_u64 v[34:35], s[70:71], 0, v[32:33]
	global_load_dword v242, v[34:35], off nt
	v_lshl_add_u64 v[34:35], s[62:63], 0, v[32:33]
	v_lshl_add_u64 v[32:33], s[64:65], 0, v[32:33]
	s_or_b32 s52, s84, 0xc00
	global_load_dword v114, v[34:35], off nt
	global_load_dword v115, v[32:33], off nt
	v_lshl_add_u64 v[32:33], s[52:53], 0, v[76:77]
	v_lshlrev_b64 v[32:33], 1, v[32:33]
	v_lshl_add_u64 v[34:35], s[70:71], 0, v[32:33]
	global_load_dword v243, v[34:35], off nt
	v_lshl_add_u64 v[34:35], s[62:63], 0, v[32:33]
	v_lshl_add_u64 v[32:33], s[64:65], 0, v[32:33]
	s_or_b32 s52, s84, 0x1000
	global_load_dword v116, v[34:35], off nt
	global_load_dword v117, v[32:33], off nt
	v_lshl_add_u64 v[32:33], s[52:53], 0, v[76:77]
	v_lshlrev_b64 v[32:33], 1, v[32:33]
	v_lshl_add_u64 v[34:35], s[70:71], 0, v[32:33]
	global_load_dword v244, v[34:35], off nt
	v_lshl_add_u64 v[34:35], s[62:63], 0, v[32:33]
	v_lshl_add_u64 v[32:33], s[64:65], 0, v[32:33]
	s_or_b32 s52, s84, 0x1400
	global_load_dword v118, v[34:35], off nt
	global_load_dword v119, v[32:33], off nt
	v_lshl_add_u64 v[32:33], s[52:53], 0, v[76:77]
	v_lshlrev_b64 v[32:33], 1, v[32:33]
	v_lshl_add_u64 v[34:35], s[70:71], 0, v[32:33]
	global_load_dword v245, v[34:35], off nt
	v_lshl_add_u64 v[34:35], s[62:63], 0, v[32:33]
	v_lshl_add_u64 v[32:33], s[64:65], 0, v[32:33]
	s_or_b32 s52, s84, 0x1800
	global_load_dword v120, v[34:35], off nt
	global_load_dword v121, v[32:33], off nt
	v_lshl_add_u64 v[32:33], s[52:53], 0, v[76:77]
	v_lshlrev_b64 v[32:33], 1, v[32:33]
	v_lshl_add_u64 v[34:35], s[70:71], 0, v[32:33]
	global_load_dword v246, v[34:35], off nt
	v_lshl_add_u64 v[34:35], s[62:63], 0, v[32:33]
	v_lshl_add_u64 v[32:33], s[64:65], 0, v[32:33]
	s_or_b32 s52, s84, 0x1c00
	global_load_dword v122, v[34:35], off nt
	global_load_dword v123, v[32:33], off nt
	v_lshl_add_u64 v[32:33], s[52:53], 0, v[76:77]
	v_lshlrev_b64 v[32:33], 1, v[32:33]
	v_lshl_add_u64 v[34:35], s[70:71], 0, v[32:33]
	global_load_dword v247, v[34:35], off nt
	v_add_co_u32_e32 v38, vcc, 0x13420000, v102
	s_mov_b64 s[52:53], 0x13420000
	s_nop 0
	v_addc_co_u32_e32 v39, vcc, 0, v103, vcc
	v_lshl_add_u64 v[34:35], s[62:63], 0, v[32:33]
	v_lshl_add_u64 v[32:33], s[64:65], 0, v[32:33]
	v_lshl_add_u64 v[36:37], v[102:103], 0, s[52:53]
	global_load_dwordx4 v[56:59], v[38:39], off nt
	global_load_dword v124, v[34:35], off nt
	global_load_dword v125, v[32:33], off nt
	global_load_dwordx4 v[60:63], v[36:37], off offset:16 nt
